# attention QK section: counted lgkmcnt waits per K fragment
# baseline (speedup 1.0000x reference)
.LBB0_185:
	ds_read_b128 v[126:129], v244 offset:16384
	s_waitcnt lgkmcnt(1)
	v_mfma_f32_32x32x16_bf16 v[82:97], v[98:101], v[146:149], v[66:81]
	ds_read_b128 v[122:125], v240 offset:24576
	v_mfma_f32_32x32x16_bf16 v[98:113], v[114:117], v[146:149], v[66:81]
	ds_read_b128 v[114:117], v241 offset:16384
	v_mfma_f32_32x32x16_bf16 v[82:97], v[118:121], v[150:153], v[82:97]
	ds_read_b128 v[118:121], v241 offset:24576
	s_waitcnt lgkmcnt(2)
	v_mfma_f32_32x32x16_bf16 v[98:113], v[122:125], v[150:153], v[98:113]
	ds_read_b128 v[122:125], v243 offset:16384
	s_waitcnt lgkmcnt(2)
	v_mfma_f32_32x32x16_bf16 v[82:97], v[114:117], v[154:157], v[82:97]
	ds_read_b128 v[114:117], v243 offset:24576
	s_waitcnt lgkmcnt(2)
	v_mfma_f32_32x32x16_bf16 v[98:113], v[118:121], v[154:157], v[98:113]
	s_waitcnt lgkmcnt(1)
	v_mfma_f32_32x32x16_bf16 v[82:97], v[122:125], v[158:161], v[82:97]
	s_waitcnt lgkmcnt(0)
	v_mfma_f32_32x32x16_bf16 v[98:113], v[114:117], v[158:161], v[98:113]
	s_nop 0
	ds_read_b128 v[122:125], v244 offset:20480
	ds_read_b128 v[118:121], v244 offset:24576
	ds_read_b128 v[114:117], v244 offset:28672
	s_add_i32 s22, s21, 64
	s_cmp_le_u32 s22, s20
	s_cbranch_scc0 .Lnear_u1e

.LBB0_225:
	ds_read_b128 v[126:129], v244 offset:32768
	s_waitcnt lgkmcnt(1)
	v_mfma_f32_32x32x16_bf16 v[82:97], v[98:101], v[146:149], v[66:81]
	ds_read_b128 v[122:125], v240 offset:40960
	v_mfma_f32_32x32x16_bf16 v[98:113], v[114:117], v[146:149], v[66:81]
	ds_read_b128 v[114:117], v241 offset:32768
	v_mfma_f32_32x32x16_bf16 v[82:97], v[118:121], v[150:153], v[82:97]
	ds_read_b128 v[118:121], v241 offset:40960
	s_waitcnt lgkmcnt(2)
	v_mfma_f32_32x32x16_bf16 v[98:113], v[122:125], v[150:153], v[98:113]
	ds_read_b128 v[122:125], v243 offset:32768
	s_waitcnt lgkmcnt(2)
	v_mfma_f32_32x32x16_bf16 v[82:97], v[114:117], v[154:157], v[82:97]
	ds_read_b128 v[114:117], v243 offset:40960
	s_waitcnt lgkmcnt(2)
	v_mfma_f32_32x32x16_bf16 v[98:113], v[118:121], v[154:157], v[98:113]
	s_waitcnt lgkmcnt(1)
	v_mfma_f32_32x32x16_bf16 v[82:97], v[122:125], v[158:161], v[82:97]
	s_waitcnt lgkmcnt(0)
	v_mfma_f32_32x32x16_bf16 v[98:113], v[114:117], v[158:161], v[98:113]
	s_nop 0
	ds_read_b128 v[122:125], v244 offset:36864
	ds_read_b128 v[118:121], v244 offset:40960
	ds_read_b128 v[114:117], v244 offset:45056
	s_add_i32 s26, s21, 0x80
	s_cmp_le_u32 s26, s20
	s_cbranch_scc0 .Lnear_u1o

.Lr1u1_LBB0_185:
	ds_read_b128 v[126:129], v244 offset:49152
	s_waitcnt lgkmcnt(1)
	v_mfma_f32_32x32x16_bf16 v[82:97], v[98:101], v[146:149], v[66:81]
	ds_read_b128 v[122:125], v240 offset:8192
	v_mfma_f32_32x32x16_bf16 v[98:113], v[114:117], v[146:149], v[66:81]
	ds_read_b128 v[114:117], v241
	v_mfma_f32_32x32x16_bf16 v[82:97], v[118:121], v[150:153], v[82:97]
	ds_read_b128 v[118:121], v241 offset:8192
	s_waitcnt lgkmcnt(2)
	v_mfma_f32_32x32x16_bf16 v[98:113], v[122:125], v[150:153], v[98:113]
	ds_read_b128 v[122:125], v243
	s_waitcnt lgkmcnt(2)
	v_mfma_f32_32x32x16_bf16 v[82:97], v[114:117], v[154:157], v[82:97]
	ds_read_b128 v[114:117], v243 offset:8192
	s_waitcnt lgkmcnt(2)
	v_mfma_f32_32x32x16_bf16 v[98:113], v[118:121], v[154:157], v[98:113]
	s_waitcnt lgkmcnt(1)
	v_mfma_f32_32x32x16_bf16 v[82:97], v[122:125], v[158:161], v[82:97]
	s_waitcnt lgkmcnt(0)
	v_mfma_f32_32x32x16_bf16 v[98:113], v[114:117], v[158:161], v[98:113]
	s_nop 0
	ds_read_b128 v[122:125], v244 offset:53248
	ds_read_b128 v[118:121], v244 offset:57344
	ds_read_b128 v[114:117], v244 offset:61440
	s_add_i32 s22, s21, 64
	s_cmp_le_u32 s22, s20
	s_cbranch_scc0 .Lr1u1_Lnear_u1e

.Lr1u1_LBB0_225:
	ds_read_b128 v[126:129], v244 offset:16384
	s_waitcnt lgkmcnt(1)
	v_mfma_f32_32x32x16_bf16 v[82:97], v[98:101], v[146:149], v[66:81]
	ds_read_b128 v[122:125], v240 offset:24576
	v_mfma_f32_32x32x16_bf16 v[98:113], v[114:117], v[146:149], v[66:81]
	ds_read_b128 v[114:117], v241 offset:16384
	v_mfma_f32_32x32x16_bf16 v[82:97], v[118:121], v[150:153], v[82:97]
	ds_read_b128 v[118:121], v241 offset:24576
	s_waitcnt lgkmcnt(2)
	v_mfma_f32_32x32x16_bf16 v[98:113], v[122:125], v[150:153], v[98:113]
	ds_read_b128 v[122:125], v243 offset:16384
	s_waitcnt lgkmcnt(2)
	v_mfma_f32_32x32x16_bf16 v[82:97], v[114:117], v[154:157], v[82:97]
	ds_read_b128 v[114:117], v243 offset:24576
	s_waitcnt lgkmcnt(2)
	v_mfma_f32_32x32x16_bf16 v[98:113], v[118:121], v[154:157], v[98:113]
	s_waitcnt lgkmcnt(1)
	v_mfma_f32_32x32x16_bf16 v[82:97], v[122:125], v[158:161], v[82:97]
	s_waitcnt lgkmcnt(0)
	v_mfma_f32_32x32x16_bf16 v[98:113], v[114:117], v[158:161], v[98:113]
	s_nop 0
	ds_read_b128 v[122:125], v244 offset:20480
	ds_read_b128 v[118:121], v244 offset:24576
	ds_read_b128 v[114:117], v244 offset:28672
	s_add_i32 s26, s21, 0x80
	s_cmp_le_u32 s26, s20
	s_cbranch_scc0 .Lr1u1_Lnear_u1o

.Lr2u1_LBB0_185:
	ds_read_b128 v[126:129], v244 offset:32768
	s_waitcnt lgkmcnt(1)
	v_mfma_f32_32x32x16_bf16 v[82:97], v[98:101], v[146:149], v[66:81]
	ds_read_b128 v[122:125], v240 offset:40960
	v_mfma_f32_32x32x16_bf16 v[98:113], v[114:117], v[146:149], v[66:81]
	ds_read_b128 v[114:117], v241 offset:32768
	v_mfma_f32_32x32x16_bf16 v[82:97], v[118:121], v[150:153], v[82:97]
	ds_read_b128 v[118:121], v241 offset:40960
	s_waitcnt lgkmcnt(2)
	v_mfma_f32_32x32x16_bf16 v[98:113], v[122:125], v[150:153], v[98:113]
	ds_read_b128 v[122:125], v243 offset:32768
	s_waitcnt lgkmcnt(2)
	v_mfma_f32_32x32x16_bf16 v[82:97], v[114:117], v[154:157], v[82:97]
	ds_read_b128 v[114:117], v243 offset:40960
	s_waitcnt lgkmcnt(2)
	v_mfma_f32_32x32x16_bf16 v[98:113], v[118:121], v[154:157], v[98:113]
	s_waitcnt lgkmcnt(1)
	v_mfma_f32_32x32x16_bf16 v[82:97], v[122:125], v[158:161], v[82:97]
	s_waitcnt lgkmcnt(0)
	v_mfma_f32_32x32x16_bf16 v[98:113], v[114:117], v[158:161], v[98:113]
	s_nop 0
	ds_read_b128 v[122:125], v244 offset:36864
	ds_read_b128 v[118:121], v244 offset:40960
	ds_read_b128 v[114:117], v244 offset:45056
	s_add_i32 s22, s21, 64
	s_cmp_le_u32 s22, s20
	s_cbranch_scc0 .Lr2u1_Lnear_u1e

.Lr2u1_LBB0_225:
	ds_read_b128 v[126:129], v244 offset:49152
	s_waitcnt lgkmcnt(1)
	v_mfma_f32_32x32x16_bf16 v[82:97], v[98:101], v[146:149], v[66:81]
	ds_read_b128 v[122:125], v240 offset:8192
	v_mfma_f32_32x32x16_bf16 v[98:113], v[114:117], v[146:149], v[66:81]
	ds_read_b128 v[114:117], v241
	v_mfma_f32_32x32x16_bf16 v[82:97], v[118:121], v[150:153], v[82:97]
	ds_read_b128 v[118:121], v241 offset:8192
	s_waitcnt lgkmcnt(2)
	v_mfma_f32_32x32x16_bf16 v[98:113], v[122:125], v[150:153], v[98:113]
	ds_read_b128 v[122:125], v243
	s_waitcnt lgkmcnt(2)
	v_mfma_f32_32x32x16_bf16 v[82:97], v[114:117], v[154:157], v[82:97]
	ds_read_b128 v[114:117], v243 offset:8192
	s_waitcnt lgkmcnt(2)
	v_mfma_f32_32x32x16_bf16 v[98:113], v[118:121], v[154:157], v[98:113]
	s_waitcnt lgkmcnt(1)
	v_mfma_f32_32x32x16_bf16 v[82:97], v[122:125], v[158:161], v[82:97]
	s_waitcnt lgkmcnt(0)
	v_mfma_f32_32x32x16_bf16 v[98:113], v[114:117], v[158:161], v[98:113]
	s_nop 0
	ds_read_b128 v[122:125], v244 offset:53248
	ds_read_b128 v[118:121], v244 offset:57344
	ds_read_b128 v[114:117], v244 offset:61440
	s_add_i32 s26, s21, 0x80
	s_cmp_le_u32 s26, s20
	s_cbranch_scc0 .Lr2u1_Lnear_u1o

.LBB0_288:
	ds_read_b128 v[126:129], v245 offset:16384
	s_waitcnt lgkmcnt(1)
	v_mfma_f32_32x32x16_bf16 v[82:97], v[98:101], v[146:149], v[66:81]
	ds_read_b128 v[122:125], v240 offset:24576
	v_mfma_f32_32x32x16_bf16 v[98:113], v[114:117], v[146:149], v[66:81]
	ds_read_b128 v[114:117], v241 offset:16384
	v_mfma_f32_32x32x16_bf16 v[82:97], v[118:121], v[150:153], v[82:97]
	ds_read_b128 v[118:121], v241 offset:24576
	s_waitcnt lgkmcnt(2)
	v_mfma_f32_32x32x16_bf16 v[98:113], v[122:125], v[150:153], v[98:113]
	ds_read_b128 v[122:125], v242 offset:16384
	s_waitcnt lgkmcnt(2)
	v_mfma_f32_32x32x16_bf16 v[82:97], v[114:117], v[154:157], v[82:97]
	ds_read_b128 v[114:117], v242 offset:24576
	s_waitcnt lgkmcnt(2)
	v_mfma_f32_32x32x16_bf16 v[98:113], v[118:121], v[154:157], v[98:113]
	s_waitcnt lgkmcnt(1)
	v_mfma_f32_32x32x16_bf16 v[82:97], v[122:125], v[158:161], v[82:97]
	s_waitcnt lgkmcnt(0)
	v_mfma_f32_32x32x16_bf16 v[98:113], v[114:117], v[158:161], v[98:113]
	s_nop 0
	ds_read_b128 v[122:125], v245 offset:20480
	ds_read_b128 v[118:121], v245 offset:24576
	ds_read_b128 v[114:117], v245 offset:28672
	s_cmp_le_u32 s20, s16
	s_cbranch_scc0 .Lnear_u2e

.LBB0_328:
	ds_read_b128 v[126:129], v245 offset:32768
	s_waitcnt lgkmcnt(1)
	v_mfma_f32_32x32x16_bf16 v[82:97], v[98:101], v[146:149], v[66:81]
	ds_read_b128 v[122:125], v240 offset:40960
	v_mfma_f32_32x32x16_bf16 v[98:113], v[114:117], v[146:149], v[66:81]
	ds_read_b128 v[114:117], v241 offset:32768
	v_mfma_f32_32x32x16_bf16 v[82:97], v[118:121], v[150:153], v[82:97]
	ds_read_b128 v[118:121], v241 offset:40960
	s_waitcnt lgkmcnt(2)
	v_mfma_f32_32x32x16_bf16 v[98:113], v[122:125], v[150:153], v[98:113]
	ds_read_b128 v[122:125], v242 offset:32768
	s_waitcnt lgkmcnt(2)
	v_mfma_f32_32x32x16_bf16 v[82:97], v[114:117], v[154:157], v[82:97]
	ds_read_b128 v[114:117], v242 offset:40960
	s_waitcnt lgkmcnt(2)
	v_mfma_f32_32x32x16_bf16 v[98:113], v[118:121], v[154:157], v[98:113]
	s_waitcnt lgkmcnt(1)
	v_mfma_f32_32x32x16_bf16 v[82:97], v[122:125], v[158:161], v[82:97]
	s_waitcnt lgkmcnt(0)
	v_mfma_f32_32x32x16_bf16 v[98:113], v[114:117], v[158:161], v[98:113]
	s_nop 0
	ds_read_b128 v[122:125], v245 offset:36864
	ds_read_b128 v[118:121], v245 offset:40960
	ds_read_b128 v[114:117], v245 offset:45056
	s_add_i32 s26, s20, 64
	s_cmp_le_u32 s26, s16
	s_cbranch_scc0 .Lnear_u2o

.Lr1u2_LBB0_288:
	ds_read_b128 v[126:129], v245 offset:49152
	s_waitcnt lgkmcnt(1)
	v_mfma_f32_32x32x16_bf16 v[82:97], v[98:101], v[146:149], v[66:81]
	ds_read_b128 v[122:125], v240 offset:8192
	v_mfma_f32_32x32x16_bf16 v[98:113], v[114:117], v[146:149], v[66:81]
	ds_read_b128 v[114:117], v241
	v_mfma_f32_32x32x16_bf16 v[82:97], v[118:121], v[150:153], v[82:97]
	ds_read_b128 v[118:121], v241 offset:8192
	s_waitcnt lgkmcnt(2)
	v_mfma_f32_32x32x16_bf16 v[98:113], v[122:125], v[150:153], v[98:113]
	ds_read_b128 v[122:125], v242
	s_waitcnt lgkmcnt(2)
	v_mfma_f32_32x32x16_bf16 v[82:97], v[114:117], v[154:157], v[82:97]
	ds_read_b128 v[114:117], v242 offset:8192
	s_waitcnt lgkmcnt(2)
	v_mfma_f32_32x32x16_bf16 v[98:113], v[118:121], v[154:157], v[98:113]
	s_waitcnt lgkmcnt(1)
	v_mfma_f32_32x32x16_bf16 v[82:97], v[122:125], v[158:161], v[82:97]
	s_waitcnt lgkmcnt(0)
	v_mfma_f32_32x32x16_bf16 v[98:113], v[114:117], v[158:161], v[98:113]
	s_nop 0
	ds_read_b128 v[122:125], v245 offset:53248
	ds_read_b128 v[118:121], v245 offset:57344
	ds_read_b128 v[114:117], v245 offset:61440
	s_cmp_le_u32 s20, s16
	s_cbranch_scc0 .Lr1u2_Lnear_u2e

.Lr1u2_LBB0_328:
	ds_read_b128 v[126:129], v245 offset:16384
	s_waitcnt lgkmcnt(1)
	v_mfma_f32_32x32x16_bf16 v[82:97], v[98:101], v[146:149], v[66:81]
	ds_read_b128 v[122:125], v240 offset:24576
	v_mfma_f32_32x32x16_bf16 v[98:113], v[114:117], v[146:149], v[66:81]
	ds_read_b128 v[114:117], v241 offset:16384
	v_mfma_f32_32x32x16_bf16 v[82:97], v[118:121], v[150:153], v[82:97]
	ds_read_b128 v[118:121], v241 offset:24576
	s_waitcnt lgkmcnt(2)
	v_mfma_f32_32x32x16_bf16 v[98:113], v[122:125], v[150:153], v[98:113]
	ds_read_b128 v[122:125], v242 offset:16384
	s_waitcnt lgkmcnt(2)
	v_mfma_f32_32x32x16_bf16 v[82:97], v[114:117], v[154:157], v[82:97]
	ds_read_b128 v[114:117], v242 offset:24576
	s_waitcnt lgkmcnt(2)
	v_mfma_f32_32x32x16_bf16 v[98:113], v[118:121], v[154:157], v[98:113]
	s_waitcnt lgkmcnt(1)
	v_mfma_f32_32x32x16_bf16 v[82:97], v[122:125], v[158:161], v[82:97]
	s_waitcnt lgkmcnt(0)
	v_mfma_f32_32x32x16_bf16 v[98:113], v[114:117], v[158:161], v[98:113]
	s_nop 0
	ds_read_b128 v[122:125], v245 offset:20480
	ds_read_b128 v[118:121], v245 offset:24576
	ds_read_b128 v[114:117], v245 offset:28672
	s_add_i32 s26, s20, 64
	s_cmp_le_u32 s26, s16
	s_cbranch_scc0 .Lr1u2_Lnear_u2o

.Lr2u2_LBB0_288:
	ds_read_b128 v[126:129], v245 offset:32768
	s_waitcnt lgkmcnt(1)
	v_mfma_f32_32x32x16_bf16 v[82:97], v[98:101], v[146:149], v[66:81]
	ds_read_b128 v[122:125], v240 offset:40960
	v_mfma_f32_32x32x16_bf16 v[98:113], v[114:117], v[146:149], v[66:81]
	ds_read_b128 v[114:117], v241 offset:32768
	v_mfma_f32_32x32x16_bf16 v[82:97], v[118:121], v[150:153], v[82:97]
	ds_read_b128 v[118:121], v241 offset:40960
	s_waitcnt lgkmcnt(2)
	v_mfma_f32_32x32x16_bf16 v[98:113], v[122:125], v[150:153], v[98:113]
	ds_read_b128 v[122:125], v242 offset:32768
	s_waitcnt lgkmcnt(2)
	v_mfma_f32_32x32x16_bf16 v[82:97], v[114:117], v[154:157], v[82:97]
	ds_read_b128 v[114:117], v242 offset:40960
	s_waitcnt lgkmcnt(2)
	v_mfma_f32_32x32x16_bf16 v[98:113], v[118:121], v[154:157], v[98:113]
	s_waitcnt lgkmcnt(1)
	v_mfma_f32_32x32x16_bf16 v[82:97], v[122:125], v[158:161], v[82:97]
	s_waitcnt lgkmcnt(0)
	v_mfma_f32_32x32x16_bf16 v[98:113], v[114:117], v[158:161], v[98:113]
	s_nop 0
	ds_read_b128 v[122:125], v245 offset:36864
	ds_read_b128 v[118:121], v245 offset:40960
	ds_read_b128 v[114:117], v245 offset:45056
	s_cmp_le_u32 s20, s16
	s_cbranch_scc0 .Lr2u2_Lnear_u2e

.Lr2u2_LBB0_328:
	ds_read_b128 v[126:129], v245 offset:49152
	s_waitcnt lgkmcnt(1)
	v_mfma_f32_32x32x16_bf16 v[82:97], v[98:101], v[146:149], v[66:81]
	ds_read_b128 v[122:125], v240 offset:8192
	v_mfma_f32_32x32x16_bf16 v[98:113], v[114:117], v[146:149], v[66:81]
	ds_read_b128 v[114:117], v241
	v_mfma_f32_32x32x16_bf16 v[82:97], v[118:121], v[150:153], v[82:97]
	ds_read_b128 v[118:121], v241 offset:8192
	s_waitcnt lgkmcnt(2)
	v_mfma_f32_32x32x16_bf16 v[98:113], v[122:125], v[150:153], v[98:113]
	ds_read_b128 v[122:125], v242
	s_waitcnt lgkmcnt(2)
	v_mfma_f32_32x32x16_bf16 v[82:97], v[114:117], v[154:157], v[82:97]
	ds_read_b128 v[114:117], v242 offset:8192
	s_waitcnt lgkmcnt(2)
	v_mfma_f32_32x32x16_bf16 v[98:113], v[118:121], v[154:157], v[98:113]
	s_waitcnt lgkmcnt(1)
	v_mfma_f32_32x32x16_bf16 v[82:97], v[122:125], v[158:161], v[82:97]
	s_waitcnt lgkmcnt(0)
	v_mfma_f32_32x32x16_bf16 v[98:113], v[114:117], v[158:161], v[98:113]
	s_nop 0
	ds_read_b128 v[122:125], v245 offset:53248
	ds_read_b128 v[118:121], v245 offset:57344
	ds_read_b128 v[114:117], v245 offset:61440
	s_add_i32 s26, s20, 64
	s_cmp_le_u32 s26, s16
	s_cbranch_scc0 .Lr2u2_Lnear_u2o
